# early duplicate kernarg loads at entry, on top of flag-merged barriers 4 and 9 and direct TOPGEN polling
# baseline (speedup 1.0000x reference)
; #define LAS __attribute__((address_space(3)))
; __global__ void __launch_bounds__(NTHR, 2) fwd_megakernel(Args args) {
;     extern __shared__ __attribute__((aligned(16))) unsigned char lds_raw[];
;     LAS unsigned char* lds = (LAS unsigned char*)lds_raw;
;     cg::grid_group grid = cg::this_grid();
;     if (gridDim.x == 0x7fffffffu) grid.sync();
_Z14fwd_megakernel4Args:
	s_load_dwordx2 s[6:7], s[0:1], 0x90
	s_load_dwordx16 s[68:83], s[0:1], 0x0
	s_load_dwordx16 s[52:67], s[0:1], 0x40
	s_add_u32 s8, s0, 0x90
	s_addc_u32 s9, s1, 0
	s_waitcnt lgkmcnt(0)
	s_cmp_eq_u32 s6, 0x7fffffff
	s_cbranch_scc1 .LBB0_2
	v_and_b32_e32 v216, 0x3ff, v0
	s_load_dword s3, s[0:1], 0x98
	s_cbranch_execz .LBB0_3
	s_branch .LBB0_14
